# p5x + decode mLSTM q/k/v/n staging: four loads in flight, one wait (was 3 dependent round trips)
# baseline (speedup 1.0000x reference)
.LBB0_537:
	s_ashr_i32 s0, s44, 2
	s_add_i32 s56, s0, 0x4000
	s_and_b32 s59, s44, 2
	s_ashr_i32 s57, s56, 31
	s_ashr_i32 s45, s44, 31
	s_and_saveexec_b64 s[0:1], s[2:3]
	s_cbranch_execz .LBB0_539
	s_lshl_b64 s[8:9], s[56:57], 10
	s_lshl_b32 vcc_lo, s59, 8
	s_or_b32 s8, s8, vcc_lo
	v_lshl_add_u64 v[130:131], s[8:9], 0, v[146:147]
	v_lshlrev_b64 v[130:131], 1, v[130:131]
	v_lshl_add_u64 v[132:133], s[10:11], 0, v[130:131]
	global_load_ushort v184, v[132:133], off
	v_readlane_b32 s4, v245, 46
	v_readlane_b32 s5, v245, 47
	s_lshl_b64 s[8:9], s[44:45], 10
	s_nop 1
	v_lshl_add_u64 v[132:133], s[4:5], 0, v[130:131]
	global_load_ushort v185, v[132:133], off
	v_readlane_b32 s4, v245, 57
	v_readlane_b32 s5, v245, 58
	s_nop 2
	v_lshl_add_u64 v[132:133], s[4:5], 0, v[130:131]
	global_load_ushort v186, v[132:133], off
	v_lshl_add_u64 v[130:131], v[150:151], 0, s[8:9]
	global_load_dword v187, v[130:131], off
	s_waitcnt vmcnt(0)
	v_lshlrev_b32_e32 v184, 16, v184
	v_lshlrev_b32_e32 v185, 16, v185
	v_lshlrev_b32_e32 v186, 16, v186
	ds_write2st64_b32 v1, v184, v185 offset1:4
	ds_write2st64_b32 v1, v186, v187 offset0:8 offset1:12

.LBB0_795:
	v_readlane_b32 s0, v245, 61
	s_add_i32 s0, s0, s22
	s_ashr_i32 s1, s0, 2
	s_add_i32 s72, s1, 0x4000
	s_and_b32 s24, s0, 3
	s_ashr_i32 s73, s72, 31
	s_ashr_i32 s1, s0, 31
	s_and_saveexec_b64 s[8:9], s[2:3]
	s_cbranch_execz .LBB0_797
	s_lshl_b64 s[74:75], s[72:73], 10
	s_lshl_b32 s25, s24, 8
	s_or_b32 s74, s74, s25
	v_lshl_add_u64 v[130:131], s[74:75], 0, v[146:147]
	v_readlane_b32 s36, v245, 57
	v_lshlrev_b64 v[130:131], 1, v[130:131]
	v_readlane_b32 s37, v245, 58
	s_lshl_b64 s[74:75], s[0:1], 10
	s_nop 1
	v_lshl_add_u64 v[132:133], s[36:37], 0, v[130:131]
	global_load_ushort v184, v[132:133], off
	v_readlane_b32 s36, v244, 19
	v_readlane_b32 s37, v244, 20
	s_nop 2
	v_lshl_add_u64 v[132:133], s[36:37], 0, v[130:131]
	global_load_ushort v185, v[132:133], off
	v_readlane_b32 s36, v244, 24
	v_readlane_b32 s37, v244, 25
	s_nop 2
	v_lshl_add_u64 v[132:133], s[36:37], 0, v[130:131]
	global_load_ushort v186, v[132:133], off
	v_lshl_add_u64 v[130:131], v[152:153], 0, s[74:75]
	global_load_dword v187, v[130:131], off
	s_waitcnt vmcnt(0)
	v_lshlrev_b32_e32 v184, 16, v184
	v_lshlrev_b32_e32 v185, 16, v185
	v_lshlrev_b32_e32 v186, 16, v186
	ds_write2st64_b32 v166, v184, v185 offset1:4
	ds_write2st64_b32 v166, v186, v187 offset0:8 offset1:12
